# unit boundary: trailing half's restore barrier moved to the head of the next K loop (flag in s100) so S.next + zero-init overlap the wait; leading half at priority 2 for that stretch; on top of the ha
# baseline (speedup 1.0000x reference)
_Z7enc_fwd4Args:
	s_mov_b32 s100, 0
	v_lshl_add_u32 v1, v0, 2, 0
	v_add_u32_e32 v1, 0x20000, v1
	v_mov_b32_e32 v2, 0
	s_mov_b64 s[76:77], s[0:1]
	ds_write2st64_b32 v1, v2, v2 offset1:8
	ds_write2st64_b32 v1, v2, v2 offset0:16 offset1:24
	v_or_b32_e32 v1, 0x800, v0
	s_mov_b64 s[4:5], -1
	s_and_saveexec_b64 s[6:7], s[4:5]
	v_lshl_add_u32 v3, v1, 2, 0
	v_add_u32_e32 v3, 0x20000, v3
	ds_write_b32 v3, v2
	s_or_b64 exec, exec, s[6:7]
	s_and_saveexec_b64 s[6:7], s[4:5]
	s_add_i32 s0, 0, 0x20000
	v_lshl_add_u32 v1, v1, 2, s0
	v_mov_b32_e32 v2, 0
	ds_write_b32 v1, v2 offset:2048
	s_or_b64 exec, exec, s[6:7]
	v_or_b32_e32 v1, 0xc00, v0
	v_cmp_gt_u32_e64 s[4:5], 7, 6
	v_cmp_gt_u32_e64 s[0:1], 7, 5
	s_and_saveexec_b64 s[6:7], s[0:1]
	v_lshl_add_u32 v2, v1, 2, 0
	v_add_u32_e32 v2, 0x20000, v2
	v_mov_b32_e32 v3, 0
	ds_write_b32 v2, v3
	s_or_b64 exec, exec, s[6:7]
	s_load_dwordx2 s[0:1], s[76:77], 0xf8
	s_waitcnt lgkmcnt(0)
	v_writelane_b32 v254, s0, 0
	s_nop 1
	v_writelane_b32 v254, s1, 1
	s_and_saveexec_b64 s[6:7], s[4:5]
	s_add_i32 s0, 0, 0x20000
	v_lshl_add_u32 v1, v1, 2, s0
	v_mov_b32_e32 v2, 0
	ds_write_b32 v1, v2 offset:2048
	s_or_b64 exec, exec, s[6:7]
	s_waitcnt lgkmcnt(0)
	s_barrier
	s_getreg_b32 s0, hwreg(HW_REG_XCC_ID, 0, 4)
	v_cmp_eq_u32_e64 s[4:5], 0, v0
	s_mov_b64 s[6:7], exec
	s_nop 0
	v_writelane_b32 v254, s4, 2
	s_nop 1
	v_writelane_b32 v254, s5, 3
	s_and_b64 s[4:5], s[6:7], s[4:5]
	s_mov_b64 exec, s[4:5]
	s_cbranch_execz .LBB0_11
	s_mov_b64 s[8:9], exec
	v_mbcnt_lo_u32_b32 v1, s8, 0
	v_mbcnt_hi_u32_b32 v1, s9, v1
	v_cmp_eq_u32_e32 vcc, 0, v1
	s_and_b64 s[4:5], exec, vcc
	s_mov_b64 exec, s[4:5]
	s_cbranch_execz .LBB0_11
	s_load_dwordx2 s[4:5], s[76:77], 0xf0
	s_lshl_b32 s0, s0, 8
	s_and_b32 s0, s0, 0xf00
	v_mov_b32_e32 v1, 0x4000
	s_waitcnt lgkmcnt(0)
	s_add_u32 s0, s4, s0
	s_addc_u32 s1, s5, 0
	s_bcnt1_i32_b64 s3, s[8:9]
	v_mov_b32_e32 v2, s3
	global_atomic_add v1, v2, s[0:1] offset:1024

.LBB0_297:
	s_cmp_eq_u32 s100, 0
	s_cbranch_scc1 .Lx_lb_0
	s_barrier
	s_mov_b32 s100, 0

.LBB0_309:
	s_setprio 2
	s_andn2_b64 vcc, exec, s[10:11]
	s_cbranch_vccnz .LBB0_284
	s_setprio 0
	s_mov_b32 s100, 1
	s_branch .LBB0_284

.LBB0_348:
	s_setprio 2
	s_andn2_b64 vcc, exec, s[12:13]
	s_cbranch_vccnz .LBB0_331
	s_setprio 0
	s_mov_b32 s100, 1
	s_branch .LBB0_331

.LBB0_885:
	v_mov_b32_e32 v4, v2
	v_mov_b32_e32 v5, v2
	v_mov_b32_e32 v3, v2
	v_mov_b64_e32 v[8:9], v[4:5]
	v_mov_b64_e32 v[12:13], v[4:5]
	v_mov_b64_e32 v[16:17], v[4:5]
	v_mov_b64_e32 v[20:21], v[4:5]
	v_mov_b64_e32 v[24:25], v[4:5]
	v_mov_b64_e32 v[28:29], v[4:5]
	v_mov_b64_e32 v[32:33], v[4:5]
	v_mov_b64_e32 v[36:37], v[4:5]
	v_mov_b64_e32 v[40:41], v[4:5]
	v_mov_b64_e32 v[44:45], v[4:5]
	v_mov_b64_e32 v[48:49], v[4:5]
	v_mov_b64_e32 v[52:53], v[4:5]
	v_mov_b64_e32 v[56:57], v[4:5]
	v_mov_b64_e32 v[60:61], v[4:5]
	v_mov_b64_e32 v[64:65], v[4:5]
	v_mov_b64_e32 v[68:69], v[4:5]
	v_mov_b64_e32 v[72:73], v[4:5]
	v_mov_b64_e32 v[76:77], v[4:5]
	v_mov_b64_e32 v[80:81], v[4:5]
	v_mov_b64_e32 v[84:85], v[4:5]
	v_mov_b64_e32 v[88:89], v[4:5]
	v_mov_b64_e32 v[92:93], v[4:5]
	v_mov_b64_e32 v[96:97], v[4:5]
	v_mov_b64_e32 v[100:101], v[4:5]
	v_mov_b64_e32 v[104:105], v[4:5]
	v_mov_b64_e32 v[108:109], v[4:5]
	v_mov_b64_e32 v[112:113], v[4:5]
	v_mov_b64_e32 v[116:117], v[4:5]
	v_mov_b64_e32 v[120:121], v[4:5]
	v_mov_b64_e32 v[124:125], v[4:5]
	v_mov_b64_e32 v[128:129], v[4:5]
	v_mov_b64_e32 v[132:133], v[4:5]
	v_mov_b64_e32 v[6:7], v[2:3]
	v_mov_b64_e32 v[10:11], v[2:3]
	v_mov_b64_e32 v[14:15], v[2:3]
	v_mov_b64_e32 v[18:19], v[2:3]
	v_mov_b64_e32 v[22:23], v[2:3]
	v_mov_b64_e32 v[26:27], v[2:3]
	v_mov_b64_e32 v[30:31], v[2:3]
	v_mov_b64_e32 v[34:35], v[2:3]
	v_mov_b64_e32 v[38:39], v[2:3]
	v_mov_b64_e32 v[42:43], v[2:3]
	v_mov_b64_e32 v[46:47], v[2:3]
	v_mov_b64_e32 v[50:51], v[2:3]
	v_mov_b64_e32 v[54:55], v[2:3]
	v_mov_b64_e32 v[58:59], v[2:3]
	v_mov_b64_e32 v[62:63], v[2:3]
	v_mov_b64_e32 v[66:67], v[2:3]
	v_mov_b64_e32 v[70:71], v[2:3]
	v_mov_b64_e32 v[74:75], v[2:3]
	v_mov_b64_e32 v[78:79], v[2:3]
	v_mov_b64_e32 v[82:83], v[2:3]
	v_mov_b64_e32 v[86:87], v[2:3]
	v_mov_b64_e32 v[90:91], v[2:3]
	v_mov_b64_e32 v[94:95], v[2:3]
	v_mov_b64_e32 v[98:99], v[2:3]
	v_mov_b64_e32 v[102:103], v[2:3]
	v_mov_b64_e32 v[106:107], v[2:3]
	v_mov_b64_e32 v[110:111], v[2:3]
	v_mov_b64_e32 v[114:115], v[2:3]
	v_mov_b64_e32 v[118:119], v[2:3]
	v_mov_b64_e32 v[122:123], v[2:3]
	v_mov_b64_e32 v[126:127], v[2:3]
	v_mov_b64_e32 v[130:131], v[2:3]
	s_setprio 2
	s_andn2_b64 vcc, exec, s[18:19]
	s_cbranch_vccnz .LBB0_727
.LBB0_886:
	s_setprio 0
	s_mov_b32 s100, 1
	s_branch .LBB0_727

.LBB0_991:
	s_setprio 2
	s_andn2_b64 vcc, exec, s[42:43]
	s_cbranch_vccnz .LBB0_958
	s_setprio 0
	s_mov_b32 s100, 1
	s_branch .LBB0_958

.LBB0_1041:
	s_setprio 2
	s_andn2_b64 vcc, exec, s[28:29]
	s_cbranch_vccnz .LBB0_1008
	s_setprio 0
	s_mov_b32 s100, 1
	s_branch .LBB0_1008

.LBB0_1140:
	v_lshl_add_u32 v150, s63, 8, v3
	v_ashrrev_i32_e32 v151, 31, v150
	v_lshl_add_u64 v[164:165], v[150:151], 3, s[16:17]
	global_load_dwordx2 v[168:169], v[164:165], off
	v_or_b32_e32 v148, 16, v150
	v_ashrrev_i32_e32 v149, 31, v148
	v_lshl_add_u64 v[144:145], v[148:149], 3, s[16:17]
	global_load_dwordx2 v[172:173], v[144:145], off
	v_or_b32_e32 v146, 32, v150
	v_ashrrev_i32_e32 v147, 31, v146
	v_lshl_add_u64 v[144:145], v[146:147], 3, s[16:17]
	global_load_dwordx2 v[174:175], v[144:145], off
	global_load_dwordx2 v[162:163], v[164:165], off offset:1152
	v_or_b32_e32 v144, 48, v150
	v_ashrrev_i32_e32 v145, 31, v144
	v_lshl_add_u64 v[152:153], v[144:145], 3, s[16:17]
	global_load_dwordx2 v[154:155], v[152:153], off
	global_load_dwordx2 v[166:167], v[164:165], off offset:1280
	v_mov_b32_e32 v177, v2
	global_load_dwordx2 v[152:153], v[164:165], off offset:1024
	s_min_u32 s23, s72, 32
	global_load_dwordx2 v[164:165], v[164:165], off offset:1408
	s_sub_i32 s29, 32, s23
	v_add_u32_e32 v170, 0x80, v150
	v_add_u32_e32 v149, 0x90, v150
	v_add_u32_e32 v147, 0xa0, v150
	v_add_u32_e32 v145, 0xb0, v150
	s_andn2_b64 vcc, exec, s[10:11]
	s_waitcnt vmcnt(0)
	v_mov_b32_e32 v176, v169
	v_lshlrev_b64 v[176:177], s23, v[176:177]
	v_min_u32_e32 v151, 1, v176
	v_or_b32_e32 v151, v177, v151
	v_cvt_f32_u32_e32 v151, v151
	v_cvt_f32_u32_e32 v156, v168
	v_mov_b32_e32 v168, v173
	v_mov_b32_e32 v169, v2
	v_ldexp_f32 v151, v151, s29
	v_mul_f32_e32 v151, 0x43800000, v151
	v_fmac_f32_e32 v151, 0x33800000, v156
	v_fmamk_f32 v151, v151, 0x3a000000, v1
	v_lshlrev_b64 v[168:169], s23, v[168:169]
	v_rsq_f32_e32 v160, v151
	v_min_u32_e32 v151, 1, v168
	v_or_b32_e32 v151, v169, v151
	v_cvt_f32_u32_e32 v151, v151
	v_cvt_f32_u32_e32 v156, v172
	v_mov_b32_e32 v168, v175
	v_mov_b32_e32 v169, v2
	v_ldexp_f32 v151, v151, s29
	v_mul_f32_e32 v151, 0x43800000, v151
	v_fmac_f32_e32 v151, 0x33800000, v156
	v_fmamk_f32 v151, v151, 0x3a000000, v1
	v_lshlrev_b64 v[168:169], s23, v[168:169]
	v_rsq_f32_e32 v158, v151
	v_min_u32_e32 v151, 1, v168
	v_or_b32_e32 v151, v169, v151
	v_cvt_f32_u32_e32 v151, v151
	v_cvt_f32_u32_e32 v156, v174
	v_mov_b32_e32 v168, v155
	v_mov_b32_e32 v169, v2
	v_ldexp_f32 v151, v151, s29
	v_mul_f32_e32 v151, 0x43800000, v151
	v_fmac_f32_e32 v151, 0x33800000, v156
	v_fmamk_f32 v151, v151, 0x3a000000, v1
	v_lshlrev_b64 v[168:169], s23, v[168:169]
	v_rsq_f32_e32 v156, v151
	v_min_u32_e32 v151, 1, v168
	v_or_b32_e32 v151, v169, v151
	v_cvt_f32_u32_e32 v151, v151
	v_cvt_f32_u32_e32 v154, v154
	v_mov_b32_e32 v168, v153
	v_mov_b32_e32 v169, v2
	v_ldexp_f32 v151, v151, s29
	v_mul_f32_e32 v151, 0x43800000, v151
	v_fmac_f32_e32 v151, 0x33800000, v154
	v_fmamk_f32 v151, v151, 0x3a000000, v1
	v_lshlrev_b64 v[168:169], s23, v[168:169]
	v_rsq_f32_e32 v154, v151
	v_min_u32_e32 v151, 1, v168
	v_or_b32_e32 v151, v169, v151
	v_cvt_f32_u32_e32 v151, v151
	v_cvt_f32_u32_e32 v152, v152
	v_mov_b32_e32 v168, v163
	v_mov_b32_e32 v169, v2
	v_ldexp_f32 v151, v151, s29
	v_mul_f32_e32 v151, 0x43800000, v151
	v_fmac_f32_e32 v151, 0x33800000, v152
	v_fmamk_f32 v151, v151, 0x3a000000, v1
	v_lshlrev_b64 v[168:169], s23, v[168:169]
	v_rsq_f32_e32 v152, v151
	v_min_u32_e32 v151, 1, v168
	v_or_b32_e32 v151, v169, v151
	v_cvt_f32_u32_e32 v151, v151
	v_cvt_f32_u32_e32 v153, v162
	v_mov_b32_e32 v168, v167
	v_mov_b32_e32 v169, v2
	v_ldexp_f32 v151, v151, s29
	v_mul_f32_e32 v151, 0x43800000, v151
	v_fmac_f32_e32 v151, 0x33800000, v153
	v_fmamk_f32 v151, v151, 0x3a000000, v1
	v_lshlrev_b64 v[168:169], s23, v[168:169]
	v_rsq_f32_e32 v162, v151
	v_min_u32_e32 v151, 1, v168
	v_or_b32_e32 v151, v169, v151
	v_cvt_f32_u32_e32 v151, v151
	v_cvt_f32_u32_e32 v153, v166
	v_mov_b32_e32 v168, v165
	v_mov_b32_e32 v169, v2
	v_ldexp_f32 v151, v151, s29
	v_mul_f32_e32 v151, 0x43800000, v151
	v_fmac_f32_e32 v151, 0x33800000, v153
	v_fmamk_f32 v151, v151, 0x3a000000, v1
	v_lshlrev_b64 v[168:169], s23, v[168:169]
	v_rsq_f32_e32 v166, v151
	v_min_u32_e32 v151, 1, v168
	v_or_b32_e32 v151, v169, v151
	v_cvt_f32_u32_e32 v151, v151
	v_cvt_f32_u32_e32 v153, v164
	v_pk_mul_f32 v[124:125], v[124:125], v[160:161] op_sel_hi:[1,0]
	v_lshl_or_b32 v172, s62, 8, v159
	v_ldexp_f32 v151, v151, s29
	v_mul_f32_e32 v151, 0x43800000, v151
	v_fmac_f32_e32 v151, 0x33800000, v153
	v_pk_mul_f32 v[128:129], v[128:129], v[160:161] op_sel_hi:[1,0]
	v_pk_mul_f32 v[126:127], v[126:127], v[160:161] op_sel_hi:[1,0]
	v_max_f32_e32 v124, 0, v124
	v_fmamk_f32 v151, v151, 0x3a000000, v1
	v_ashrrev_i32_e32 v173, 31, v172
	v_mov_b64_e32 v[168:169], s[14:15]
	v_pk_mul_f32 v[130:131], v[130:131], v[160:161] op_sel_hi:[1,0]
	v_mul_f32_e32 v153, v124, v124
	v_max_f32_e32 v124, 0, v129
	v_max_f32_e32 v125, 0, v125
	v_max_f32_e32 v126, 0, v126
	v_rsq_f32_e32 v164, v151
	v_mad_i64_i32 v[174:175], s[30:31], v150, s48, v[168:169]
	v_lshlrev_b64 v[150:151], 1, v[172:173]
	v_max_f32_e32 v128, 0, v128
	v_mul_f32_e32 v124, v124, v124
	v_mul_f32_e32 v129, v125, v125
	v_max_f32_e32 v125, 0, v130
	v_mul_f32_e32 v130, v126, v126
	v_max_f32_e32 v126, 0, v131
	v_max_f32_e32 v127, 0, v127
	v_pk_mul_f32 v[118:119], v[118:119], v[160:161] op_sel_hi:[1,0]
	v_pk_mul_f32 v[116:117], v[116:117], v[160:161] op_sel_hi:[1,0]
	v_lshl_add_u64 v[172:173], v[174:175], 0, v[150:151]
	v_mul_f32_e32 v128, v128, v128
	v_mul_f32_e32 v125, v125, v125
	v_mul_f32_e32 v126, v126, v126
	v_mul_f32_e32 v127, v127, v127
	v_cvt_pk_bf16_f32 v124, v128, v124
	v_pk_mul_f32 v[122:123], v[122:123], v[160:161] op_sel_hi:[1,0]
	v_pk_mul_f32 v[120:121], v[120:121], v[160:161] op_sel_hi:[1,0]
	v_max_f32_e32 v116, 0, v116
	v_max_f32_e32 v117, 0, v117
	v_max_f32_e32 v118, 0, v118
	v_cvt_pk_bf16_f32 v125, v125, v126
	v_cvt_pk_bf16_f32 v126, v153, v129
	v_cvt_pk_bf16_f32 v127, v130, v127
	global_store_dwordx4 v[172:173], v[124:127], off
	v_max_f32_e32 v120, 0, v120
	v_max_f32_e32 v119, 0, v119
	v_mul_f32_e32 v124, v116, v116
	v_max_f32_e32 v116, 0, v121
	v_mul_f32_e32 v121, v117, v117
	v_max_f32_e32 v117, 0, v122
	v_mul_f32_e32 v122, v118, v118
	v_max_f32_e32 v118, 0, v123
	v_mul_f32_e32 v116, v116, v116
	v_mul_f32_e32 v117, v117, v117
	v_mul_f32_e32 v118, v118, v118
	v_pk_mul_f32 v[108:109], v[108:109], v[158:159] op_sel_hi:[1,0]
	v_mul_f32_e32 v120, v120, v120
	v_mul_f32_e32 v119, v119, v119
	v_cvt_pk_bf16_f32 v116, v120, v116
	v_cvt_pk_bf16_f32 v117, v117, v118
	v_cvt_pk_bf16_f32 v118, v124, v121
	v_pk_mul_f32 v[112:113], v[112:113], v[158:159] op_sel_hi:[1,0]
	v_pk_mul_f32 v[110:111], v[110:111], v[158:159] op_sel_hi:[1,0]
	v_max_f32_e32 v108, 0, v108
	v_cvt_pk_bf16_f32 v119, v122, v119
	global_store_dwordx4 v[172:173], v[116:119], off offset:256
	v_pk_mul_f32 v[114:115], v[114:115], v[158:159] op_sel_hi:[1,0]
	v_max_f32_e32 v109, 0, v109
	v_mul_f32_e32 v118, v108, v108
	v_max_f32_e32 v108, 0, v113
	v_max_f32_e32 v110, 0, v110
	v_mad_i64_i32 v[116:117], s[30:31], v148, s48, v[168:169]
	v_max_f32_e32 v112, 0, v112
	v_mul_f32_e32 v108, v108, v108
	v_mul_f32_e32 v113, v109, v109
	v_max_f32_e32 v109, 0, v114
	v_mul_f32_e32 v114, v110, v110
	v_max_f32_e32 v110, 0, v115
	v_max_f32_e32 v111, 0, v111
	v_pk_mul_f32 v[102:103], v[102:103], v[158:159] op_sel_hi:[1,0]
	v_pk_mul_f32 v[100:101], v[100:101], v[158:159] op_sel_hi:[1,0]
	v_lshl_add_u64 v[116:117], v[116:117], 0, v[150:151]
	v_mul_f32_e32 v112, v112, v112
	v_mul_f32_e32 v109, v109, v109
	v_mul_f32_e32 v110, v110, v110
	v_mul_f32_e32 v111, v111, v111
	v_cvt_pk_bf16_f32 v108, v112, v108
	v_pk_mul_f32 v[106:107], v[106:107], v[158:159] op_sel_hi:[1,0]
	v_pk_mul_f32 v[104:105], v[104:105], v[158:159] op_sel_hi:[1,0]
	v_max_f32_e32 v100, 0, v100
	v_max_f32_e32 v101, 0, v101
	v_max_f32_e32 v102, 0, v102
	v_cvt_pk_bf16_f32 v109, v109, v110
	v_cvt_pk_bf16_f32 v110, v118, v113
	v_cvt_pk_bf16_f32 v111, v114, v111
	global_store_dwordx4 v[116:117], v[108:111], off
	v_max_f32_e32 v104, 0, v104
	v_max_f32_e32 v103, 0, v103
	v_mul_f32_e32 v108, v100, v100
	v_max_f32_e32 v100, 0, v105
	v_mul_f32_e32 v105, v101, v101
	v_max_f32_e32 v101, 0, v106
	v_mul_f32_e32 v106, v102, v102
	v_max_f32_e32 v102, 0, v107
	v_mul_f32_e32 v100, v100, v100
	v_mul_f32_e32 v101, v101, v101
	v_mul_f32_e32 v102, v102, v102
	v_pk_mul_f32 v[92:93], v[92:93], v[156:157] op_sel_hi:[1,0]
	v_mul_f32_e32 v104, v104, v104
	v_mul_f32_e32 v103, v103, v103
	v_cvt_pk_bf16_f32 v100, v104, v100
	v_cvt_pk_bf16_f32 v101, v101, v102
	v_cvt_pk_bf16_f32 v102, v108, v105
	v_pk_mul_f32 v[96:97], v[96:97], v[156:157] op_sel_hi:[1,0]
	v_pk_mul_f32 v[94:95], v[94:95], v[156:157] op_sel_hi:[1,0]
	v_max_f32_e32 v92, 0, v92
	v_cvt_pk_bf16_f32 v103, v106, v103
	global_store_dwordx4 v[116:117], v[100:103], off offset:256
	v_pk_mul_f32 v[98:99], v[98:99], v[156:157] op_sel_hi:[1,0]
	v_max_f32_e32 v93, 0, v93
	v_mul_f32_e32 v102, v92, v92
	v_max_f32_e32 v92, 0, v97
	v_max_f32_e32 v94, 0, v94
	v_mad_i64_i32 v[100:101], s[30:31], v146, s48, v[168:169]
	v_max_f32_e32 v96, 0, v96
	v_mul_f32_e32 v92, v92, v92
	v_mul_f32_e32 v97, v93, v93
	v_max_f32_e32 v93, 0, v98
	v_mul_f32_e32 v98, v94, v94
	v_max_f32_e32 v94, 0, v99
	v_max_f32_e32 v95, 0, v95
	v_pk_mul_f32 v[86:87], v[86:87], v[156:157] op_sel_hi:[1,0]
	v_pk_mul_f32 v[84:85], v[84:85], v[156:157] op_sel_hi:[1,0]
	v_lshl_add_u64 v[100:101], v[100:101], 0, v[150:151]
	v_mul_f32_e32 v96, v96, v96
	v_mul_f32_e32 v93, v93, v93
	v_mul_f32_e32 v94, v94, v94
	v_mul_f32_e32 v95, v95, v95
	v_cvt_pk_bf16_f32 v92, v96, v92
	v_pk_mul_f32 v[90:91], v[90:91], v[156:157] op_sel_hi:[1,0]
	v_pk_mul_f32 v[88:89], v[88:89], v[156:157] op_sel_hi:[1,0]
	v_max_f32_e32 v84, 0, v84
	v_max_f32_e32 v85, 0, v85
	v_max_f32_e32 v86, 0, v86
	v_cvt_pk_bf16_f32 v93, v93, v94
	v_cvt_pk_bf16_f32 v94, v102, v97
	v_cvt_pk_bf16_f32 v95, v98, v95
	global_store_dwordx4 v[100:101], v[92:95], off
	v_max_f32_e32 v88, 0, v88
	v_max_f32_e32 v87, 0, v87
	v_mul_f32_e32 v92, v84, v84
	v_max_f32_e32 v84, 0, v89
	v_mul_f32_e32 v89, v85, v85
	v_max_f32_e32 v85, 0, v90
	v_mul_f32_e32 v90, v86, v86
	v_max_f32_e32 v86, 0, v91
	v_mul_f32_e32 v84, v84, v84
	v_mul_f32_e32 v85, v85, v85
	v_mul_f32_e32 v86, v86, v86
	v_pk_mul_f32 v[76:77], v[76:77], v[154:155] op_sel_hi:[1,0]
	v_mul_f32_e32 v88, v88, v88
	v_mul_f32_e32 v87, v87, v87
	v_cvt_pk_bf16_f32 v84, v88, v84
	v_cvt_pk_bf16_f32 v85, v85, v86
	v_cvt_pk_bf16_f32 v86, v92, v89
	v_pk_mul_f32 v[80:81], v[80:81], v[154:155] op_sel_hi:[1,0]
	v_pk_mul_f32 v[78:79], v[78:79], v[154:155] op_sel_hi:[1,0]
	v_max_f32_e32 v76, 0, v76
	v_cvt_pk_bf16_f32 v87, v90, v87
	global_store_dwordx4 v[100:101], v[84:87], off offset:256
	v_pk_mul_f32 v[82:83], v[82:83], v[154:155] op_sel_hi:[1,0]
	v_max_f32_e32 v77, 0, v77
	v_mul_f32_e32 v86, v76, v76
	v_max_f32_e32 v76, 0, v81
	v_max_f32_e32 v78, 0, v78
	v_mad_i64_i32 v[84:85], s[30:31], v144, s48, v[168:169]
	v_max_f32_e32 v80, 0, v80
	v_mul_f32_e32 v76, v76, v76
	v_mul_f32_e32 v81, v77, v77
	v_max_f32_e32 v77, 0, v82
	v_mul_f32_e32 v82, v78, v78
	v_max_f32_e32 v78, 0, v83
	v_max_f32_e32 v79, 0, v79
	v_pk_mul_f32 v[70:71], v[70:71], v[154:155] op_sel_hi:[1,0]
	v_pk_mul_f32 v[68:69], v[68:69], v[154:155] op_sel_hi:[1,0]
	v_lshl_add_u64 v[84:85], v[84:85], 0, v[150:151]
	v_mul_f32_e32 v80, v80, v80
	v_mul_f32_e32 v77, v77, v77
	v_mul_f32_e32 v78, v78, v78
	v_mul_f32_e32 v79, v79, v79
	v_cvt_pk_bf16_f32 v76, v80, v76
	v_pk_mul_f32 v[74:75], v[74:75], v[154:155] op_sel_hi:[1,0]
	v_pk_mul_f32 v[72:73], v[72:73], v[154:155] op_sel_hi:[1,0]
	v_max_f32_e32 v68, 0, v68
	v_max_f32_e32 v69, 0, v69
	v_max_f32_e32 v70, 0, v70
	v_cvt_pk_bf16_f32 v77, v77, v78
	v_cvt_pk_bf16_f32 v78, v86, v81
	v_cvt_pk_bf16_f32 v79, v82, v79
	global_store_dwordx4 v[84:85], v[76:79], off
	v_max_f32_e32 v72, 0, v72
	v_max_f32_e32 v71, 0, v71
	v_mul_f32_e32 v76, v68, v68
	v_max_f32_e32 v68, 0, v73
	v_mul_f32_e32 v73, v69, v69
	v_max_f32_e32 v69, 0, v74
	v_mul_f32_e32 v74, v70, v70
	v_max_f32_e32 v70, 0, v75
	v_mul_f32_e32 v68, v68, v68
	v_mul_f32_e32 v69, v69, v69
	v_mul_f32_e32 v70, v70, v70
	v_pk_mul_f32 v[60:61], v[60:61], v[152:153] op_sel_hi:[1,0]
	v_mul_f32_e32 v72, v72, v72
	v_mul_f32_e32 v71, v71, v71
	v_cvt_pk_bf16_f32 v68, v72, v68
	v_cvt_pk_bf16_f32 v69, v69, v70
	v_cvt_pk_bf16_f32 v70, v76, v73
	v_pk_mul_f32 v[64:65], v[64:65], v[152:153] op_sel_hi:[1,0]
	v_pk_mul_f32 v[62:63], v[62:63], v[152:153] op_sel_hi:[1,0]
	v_max_f32_e32 v60, 0, v60
	v_cvt_pk_bf16_f32 v71, v74, v71
	global_store_dwordx4 v[84:85], v[68:71], off offset:256
	v_pk_mul_f32 v[66:67], v[66:67], v[152:153] op_sel_hi:[1,0]
	v_max_f32_e32 v61, 0, v61
	v_mul_f32_e32 v70, v60, v60
	v_max_f32_e32 v60, 0, v65
	v_max_f32_e32 v62, 0, v62
	v_mad_i64_i32 v[68:69], s[30:31], v170, s48, v[168:169]
	v_max_f32_e32 v64, 0, v64
	v_mul_f32_e32 v60, v60, v60
	v_mul_f32_e32 v65, v61, v61
	v_max_f32_e32 v61, 0, v66
	v_mul_f32_e32 v66, v62, v62
	v_max_f32_e32 v62, 0, v67
	v_max_f32_e32 v63, 0, v63
	v_pk_mul_f32 v[54:55], v[54:55], v[152:153] op_sel_hi:[1,0]
	v_pk_mul_f32 v[52:53], v[52:53], v[152:153] op_sel_hi:[1,0]
	v_lshl_add_u64 v[68:69], v[68:69], 0, v[150:151]
	v_mul_f32_e32 v64, v64, v64
	v_mul_f32_e32 v61, v61, v61
	v_mul_f32_e32 v62, v62, v62
	v_mul_f32_e32 v63, v63, v63
	v_cvt_pk_bf16_f32 v60, v64, v60
	v_pk_mul_f32 v[58:59], v[58:59], v[152:153] op_sel_hi:[1,0]
	v_pk_mul_f32 v[56:57], v[56:57], v[152:153] op_sel_hi:[1,0]
	v_max_f32_e32 v52, 0, v52
	v_max_f32_e32 v53, 0, v53
	v_max_f32_e32 v54, 0, v54
	v_cvt_pk_bf16_f32 v61, v61, v62
	v_cvt_pk_bf16_f32 v62, v70, v65
	v_cvt_pk_bf16_f32 v63, v66, v63
	global_store_dwordx4 v[68:69], v[60:63], off
	v_max_f32_e32 v56, 0, v56
	v_max_f32_e32 v55, 0, v55
	v_mul_f32_e32 v60, v52, v52
	v_max_f32_e32 v52, 0, v57
	v_mul_f32_e32 v57, v53, v53
	v_max_f32_e32 v53, 0, v58
	v_mul_f32_e32 v58, v54, v54
	v_max_f32_e32 v54, 0, v59
	v_mul_f32_e32 v52, v52, v52
	v_mul_f32_e32 v53, v53, v53
	v_mul_f32_e32 v54, v54, v54
	v_pk_mul_f32 v[44:45], v[44:45], v[162:163] op_sel_hi:[1,0]
	v_mul_f32_e32 v56, v56, v56
	v_mul_f32_e32 v55, v55, v55
	v_cvt_pk_bf16_f32 v52, v56, v52
	v_cvt_pk_bf16_f32 v53, v53, v54
	v_cvt_pk_bf16_f32 v54, v60, v57
	v_pk_mul_f32 v[48:49], v[48:49], v[162:163] op_sel_hi:[1,0]
	v_pk_mul_f32 v[46:47], v[46:47], v[162:163] op_sel_hi:[1,0]
	v_max_f32_e32 v44, 0, v44
	v_cvt_pk_bf16_f32 v55, v58, v55
	global_store_dwordx4 v[68:69], v[52:55], off offset:256
	v_pk_mul_f32 v[50:51], v[50:51], v[162:163] op_sel_hi:[1,0]
	v_max_f32_e32 v45, 0, v45
	v_mul_f32_e32 v54, v44, v44
	v_max_f32_e32 v44, 0, v49
	v_max_f32_e32 v46, 0, v46
	v_mad_i64_i32 v[52:53], s[30:31], v149, s48, v[168:169]
	v_max_f32_e32 v48, 0, v48
	v_mul_f32_e32 v44, v44, v44
	v_mul_f32_e32 v49, v45, v45
	v_max_f32_e32 v45, 0, v50
	v_mul_f32_e32 v50, v46, v46
	v_max_f32_e32 v46, 0, v51
	v_max_f32_e32 v47, 0, v47
	v_pk_mul_f32 v[38:39], v[38:39], v[162:163] op_sel_hi:[1,0]
	v_pk_mul_f32 v[36:37], v[36:37], v[162:163] op_sel_hi:[1,0]
	v_lshl_add_u64 v[52:53], v[52:53], 0, v[150:151]
	v_mul_f32_e32 v48, v48, v48
	v_mul_f32_e32 v45, v45, v45
	v_mul_f32_e32 v46, v46, v46
	v_mul_f32_e32 v47, v47, v47
	v_cvt_pk_bf16_f32 v44, v48, v44
	v_pk_mul_f32 v[42:43], v[42:43], v[162:163] op_sel_hi:[1,0]
	v_pk_mul_f32 v[40:41], v[40:41], v[162:163] op_sel_hi:[1,0]
	v_max_f32_e32 v36, 0, v36
	v_max_f32_e32 v37, 0, v37
	v_max_f32_e32 v38, 0, v38
	v_cvt_pk_bf16_f32 v45, v45, v46
	v_cvt_pk_bf16_f32 v46, v54, v49
	v_cvt_pk_bf16_f32 v47, v50, v47
	global_store_dwordx4 v[52:53], v[44:47], off
	v_max_f32_e32 v40, 0, v40
	v_max_f32_e32 v39, 0, v39
	v_mul_f32_e32 v44, v36, v36
	v_max_f32_e32 v36, 0, v41
	v_mul_f32_e32 v41, v37, v37
	v_max_f32_e32 v37, 0, v42
	v_mul_f32_e32 v42, v38, v38
	v_max_f32_e32 v38, 0, v43
	v_mul_f32_e32 v36, v36, v36
	v_mul_f32_e32 v37, v37, v37
	v_mul_f32_e32 v38, v38, v38
	v_pk_mul_f32 v[28:29], v[28:29], v[166:167] op_sel_hi:[1,0]
	v_mul_f32_e32 v40, v40, v40
	v_mul_f32_e32 v39, v39, v39
	v_cvt_pk_bf16_f32 v36, v40, v36
	v_cvt_pk_bf16_f32 v37, v37, v38
	v_cvt_pk_bf16_f32 v38, v44, v41
	v_pk_mul_f32 v[32:33], v[32:33], v[166:167] op_sel_hi:[1,0]
	v_pk_mul_f32 v[30:31], v[30:31], v[166:167] op_sel_hi:[1,0]
	v_max_f32_e32 v28, 0, v28
	v_cvt_pk_bf16_f32 v39, v42, v39
	global_store_dwordx4 v[52:53], v[36:39], off offset:256
	v_pk_mul_f32 v[34:35], v[34:35], v[166:167] op_sel_hi:[1,0]
	v_max_f32_e32 v29, 0, v29
	v_mul_f32_e32 v38, v28, v28
	v_max_f32_e32 v28, 0, v33
	v_max_f32_e32 v30, 0, v30
	v_mad_i64_i32 v[36:37], s[30:31], v147, s48, v[168:169]
	v_max_f32_e32 v32, 0, v32
	v_mul_f32_e32 v28, v28, v28
	v_mul_f32_e32 v33, v29, v29
	v_max_f32_e32 v29, 0, v34
	v_mul_f32_e32 v34, v30, v30
	v_max_f32_e32 v30, 0, v35
	v_max_f32_e32 v31, 0, v31
	v_pk_mul_f32 v[22:23], v[22:23], v[166:167] op_sel_hi:[1,0]
	v_pk_mul_f32 v[20:21], v[20:21], v[166:167] op_sel_hi:[1,0]
	v_lshl_add_u64 v[36:37], v[36:37], 0, v[150:151]
	v_mul_f32_e32 v32, v32, v32
	v_mul_f32_e32 v29, v29, v29
	v_mul_f32_e32 v30, v30, v30
	v_mul_f32_e32 v31, v31, v31
	v_cvt_pk_bf16_f32 v28, v32, v28
	v_pk_mul_f32 v[26:27], v[26:27], v[166:167] op_sel_hi:[1,0]
	v_pk_mul_f32 v[24:25], v[24:25], v[166:167] op_sel_hi:[1,0]
	v_max_f32_e32 v20, 0, v20
	v_max_f32_e32 v21, 0, v21
	v_max_f32_e32 v22, 0, v22
	v_cvt_pk_bf16_f32 v29, v29, v30
	v_cvt_pk_bf16_f32 v30, v38, v33
	v_cvt_pk_bf16_f32 v31, v34, v31
	global_store_dwordx4 v[36:37], v[28:31], off
	v_max_f32_e32 v24, 0, v24
	v_max_f32_e32 v23, 0, v23
	v_mul_f32_e32 v28, v20, v20
	v_max_f32_e32 v20, 0, v25
	v_mul_f32_e32 v25, v21, v21
	v_max_f32_e32 v21, 0, v26
	v_mul_f32_e32 v26, v22, v22
	v_max_f32_e32 v22, 0, v27
	v_mul_f32_e32 v20, v20, v20
	v_mul_f32_e32 v21, v21, v21
	v_mul_f32_e32 v22, v22, v22
	v_pk_mul_f32 v[12:13], v[12:13], v[164:165] op_sel_hi:[1,0]
	v_mul_f32_e32 v24, v24, v24
	v_mul_f32_e32 v23, v23, v23
	v_cvt_pk_bf16_f32 v20, v24, v20
	v_cvt_pk_bf16_f32 v21, v21, v22
	v_cvt_pk_bf16_f32 v22, v28, v25
	v_pk_mul_f32 v[16:17], v[16:17], v[164:165] op_sel_hi:[1,0]
	v_pk_mul_f32 v[14:15], v[14:15], v[164:165] op_sel_hi:[1,0]
	v_max_f32_e32 v12, 0, v12
	v_cvt_pk_bf16_f32 v23, v26, v23
	global_store_dwordx4 v[36:37], v[20:23], off offset:256
	v_pk_mul_f32 v[18:19], v[18:19], v[164:165] op_sel_hi:[1,0]
	v_max_f32_e32 v13, 0, v13
	v_mul_f32_e32 v22, v12, v12
	v_max_f32_e32 v12, 0, v17
	v_max_f32_e32 v14, 0, v14
	v_mad_i64_i32 v[20:21], s[30:31], v145, s48, v[168:169]
	v_max_f32_e32 v16, 0, v16
	v_mul_f32_e32 v12, v12, v12
	v_mul_f32_e32 v17, v13, v13
	v_max_f32_e32 v13, 0, v18
	v_mul_f32_e32 v18, v14, v14
	v_max_f32_e32 v14, 0, v19
	v_max_f32_e32 v15, 0, v15
	v_pk_mul_f32 v[6:7], v[6:7], v[164:165] op_sel_hi:[1,0]
	v_pk_mul_f32 v[4:5], v[4:5], v[164:165] op_sel_hi:[1,0]
	v_lshl_add_u64 v[20:21], v[20:21], 0, v[150:151]
	v_mul_f32_e32 v16, v16, v16
	v_mul_f32_e32 v13, v13, v13
	v_mul_f32_e32 v14, v14, v14
	v_mul_f32_e32 v15, v15, v15
	v_cvt_pk_bf16_f32 v12, v16, v12
	v_pk_mul_f32 v[10:11], v[10:11], v[164:165] op_sel_hi:[1,0]
	v_pk_mul_f32 v[8:9], v[8:9], v[164:165] op_sel_hi:[1,0]
	v_max_f32_e32 v4, 0, v4
	v_max_f32_e32 v5, 0, v5
	v_max_f32_e32 v6, 0, v6
	v_cvt_pk_bf16_f32 v13, v13, v14
	v_cvt_pk_bf16_f32 v14, v22, v17
	v_cvt_pk_bf16_f32 v15, v18, v15
	global_store_dwordx4 v[20:21], v[12:15], off
	v_max_f32_e32 v7, 0, v7
	v_max_f32_e32 v8, 0, v8
	v_mul_f32_e32 v12, v4, v4
	v_max_f32_e32 v4, 0, v9
	v_mul_f32_e32 v9, v5, v5
	v_max_f32_e32 v5, 0, v10
	v_mul_f32_e32 v10, v6, v6
	v_max_f32_e32 v6, 0, v11
	v_mul_f32_e32 v4, v4, v4
	v_mul_f32_e32 v5, v5, v5
	v_mul_f32_e32 v6, v6, v6
	v_mul_f32_e32 v7, v7, v7
	s_mov_b64 s[30:31], -1
	v_mul_f32_e32 v8, v8, v8
	v_cvt_pk_bf16_f32 v4, v8, v4
	v_cvt_pk_bf16_f32 v5, v5, v6
	v_cvt_pk_bf16_f32 v6, v12, v9
	v_cvt_pk_bf16_f32 v7, v10, v7
	global_store_dwordx4 v[20:21], v[4:7], off offset:256
	s_cbranch_vccnz .LBB0_1129
	s_setprio 2
	s_andn2_b64 vcc, exec, s[12:13]
	s_cbranch_vccnz .LBB0_1128
	s_setprio 0
	s_mov_b32 s100, 1
	s_branch .LBB0_1128

.LBB0_1170:
	v_lshl_add_u32 v150, s64, 8, v3
	v_ashrrev_i32_e32 v151, 31, v150
	v_lshl_add_u64 v[164:165], v[150:151], 3, s[16:17]
	global_load_dwordx2 v[168:169], v[164:165], off
	v_or_b32_e32 v148, 16, v150
	v_ashrrev_i32_e32 v149, 31, v148
	v_lshl_add_u64 v[144:145], v[148:149], 3, s[16:17]
	global_load_dwordx2 v[172:173], v[144:145], off
	v_or_b32_e32 v146, 32, v150
	v_ashrrev_i32_e32 v147, 31, v146
	v_lshl_add_u64 v[144:145], v[146:147], 3, s[16:17]
	global_load_dwordx2 v[174:175], v[144:145], off
	global_load_dwordx2 v[162:163], v[164:165], off offset:1152
	v_or_b32_e32 v144, 48, v150
	v_ashrrev_i32_e32 v145, 31, v144
	v_lshl_add_u64 v[152:153], v[144:145], 3, s[16:17]
	global_load_dwordx2 v[154:155], v[152:153], off
	global_load_dwordx2 v[166:167], v[164:165], off offset:1280
	v_mov_b32_e32 v177, v2
	global_load_dwordx2 v[152:153], v[164:165], off offset:1024
	s_min_u32 s29, s72, 32
	global_load_dwordx2 v[164:165], v[164:165], off offset:1408
	s_sub_i32 s30, 32, s29
	v_add_u32_e32 v170, 0x80, v150
	v_add_u32_e32 v149, 0x90, v150
	v_add_u32_e32 v147, 0xa0, v150
	v_add_u32_e32 v145, 0xb0, v150
	s_andn2_b64 vcc, exec, s[22:23]
	s_waitcnt vmcnt(0)
	v_mov_b32_e32 v176, v169
	v_lshlrev_b64 v[176:177], s29, v[176:177]
	v_min_u32_e32 v151, 1, v176
	v_or_b32_e32 v151, v177, v151
	v_cvt_f32_u32_e32 v151, v151
	v_cvt_f32_u32_e32 v156, v168
	v_mov_b32_e32 v168, v173
	v_mov_b32_e32 v169, v2
	v_ldexp_f32 v151, v151, s30
	v_mul_f32_e32 v151, 0x43800000, v151
	v_fmac_f32_e32 v151, 0x33800000, v156
	v_fmamk_f32 v151, v151, 0x3a000000, v1
	v_lshlrev_b64 v[168:169], s29, v[168:169]
	v_rsq_f32_e32 v160, v151
	v_min_u32_e32 v151, 1, v168
	v_or_b32_e32 v151, v169, v151
	v_cvt_f32_u32_e32 v151, v151
	v_cvt_f32_u32_e32 v156, v172
	v_mov_b32_e32 v168, v175
	v_mov_b32_e32 v169, v2
	v_ldexp_f32 v151, v151, s30
	v_mul_f32_e32 v151, 0x43800000, v151
	v_fmac_f32_e32 v151, 0x33800000, v156
	v_fmamk_f32 v151, v151, 0x3a000000, v1
	v_lshlrev_b64 v[168:169], s29, v[168:169]
	v_rsq_f32_e32 v158, v151
	v_min_u32_e32 v151, 1, v168
	v_or_b32_e32 v151, v169, v151
	v_cvt_f32_u32_e32 v151, v151
	v_cvt_f32_u32_e32 v156, v174
	v_mov_b32_e32 v168, v155
	v_mov_b32_e32 v169, v2
	v_ldexp_f32 v151, v151, s30
	v_mul_f32_e32 v151, 0x43800000, v151
	v_fmac_f32_e32 v151, 0x33800000, v156
	v_fmamk_f32 v151, v151, 0x3a000000, v1
	v_lshlrev_b64 v[168:169], s29, v[168:169]
	v_rsq_f32_e32 v156, v151
	v_min_u32_e32 v151, 1, v168
	v_or_b32_e32 v151, v169, v151
	v_cvt_f32_u32_e32 v151, v151
	v_cvt_f32_u32_e32 v154, v154
	v_mov_b32_e32 v168, v153
	v_mov_b32_e32 v169, v2
	v_ldexp_f32 v151, v151, s30
	v_mul_f32_e32 v151, 0x43800000, v151
	v_fmac_f32_e32 v151, 0x33800000, v154
	v_fmamk_f32 v151, v151, 0x3a000000, v1
	v_lshlrev_b64 v[168:169], s29, v[168:169]
	v_rsq_f32_e32 v154, v151
	v_min_u32_e32 v151, 1, v168
	v_or_b32_e32 v151, v169, v151
	v_cvt_f32_u32_e32 v151, v151
	v_cvt_f32_u32_e32 v152, v152
	v_mov_b32_e32 v168, v163
	v_mov_b32_e32 v169, v2
	v_ldexp_f32 v151, v151, s30
	v_mul_f32_e32 v151, 0x43800000, v151
	v_fmac_f32_e32 v151, 0x33800000, v152
	v_fmamk_f32 v151, v151, 0x3a000000, v1
	v_lshlrev_b64 v[168:169], s29, v[168:169]
	v_rsq_f32_e32 v152, v151
	v_min_u32_e32 v151, 1, v168
	v_or_b32_e32 v151, v169, v151
	v_cvt_f32_u32_e32 v151, v151
	v_cvt_f32_u32_e32 v153, v162
	v_mov_b32_e32 v168, v167
	v_mov_b32_e32 v169, v2
	v_ldexp_f32 v151, v151, s30
	v_mul_f32_e32 v151, 0x43800000, v151
	v_fmac_f32_e32 v151, 0x33800000, v153
	v_fmamk_f32 v151, v151, 0x3a000000, v1
	v_lshlrev_b64 v[168:169], s29, v[168:169]
	v_rsq_f32_e32 v162, v151
	v_min_u32_e32 v151, 1, v168
	v_or_b32_e32 v151, v169, v151
	v_cvt_f32_u32_e32 v151, v151
	v_cvt_f32_u32_e32 v153, v166
	v_mov_b32_e32 v168, v165
	v_mov_b32_e32 v169, v2
	v_ldexp_f32 v151, v151, s30
	v_mul_f32_e32 v151, 0x43800000, v151
	v_fmac_f32_e32 v151, 0x33800000, v153
	v_fmamk_f32 v151, v151, 0x3a000000, v1
	v_lshlrev_b64 v[168:169], s29, v[168:169]
	v_rsq_f32_e32 v166, v151
	v_min_u32_e32 v151, 1, v168
	v_or_b32_e32 v151, v169, v151
	v_cvt_f32_u32_e32 v151, v151
	v_cvt_f32_u32_e32 v153, v164
	v_pk_mul_f32 v[124:125], v[124:125], v[160:161] op_sel_hi:[1,0]
	v_lshl_or_b32 v172, s63, 8, v159
	v_ldexp_f32 v151, v151, s30
	v_mul_f32_e32 v151, 0x43800000, v151
	v_fmac_f32_e32 v151, 0x33800000, v153
	v_pk_mul_f32 v[128:129], v[128:129], v[160:161] op_sel_hi:[1,0]
	v_pk_mul_f32 v[126:127], v[126:127], v[160:161] op_sel_hi:[1,0]
	v_max_f32_e32 v124, 0, v124
	v_fmamk_f32 v151, v151, 0x3a000000, v1
	v_ashrrev_i32_e32 v173, 31, v172
	v_mov_b64_e32 v[168:169], s[14:15]
	v_pk_mul_f32 v[130:131], v[130:131], v[160:161] op_sel_hi:[1,0]
	v_mul_f32_e32 v153, v124, v124
	v_max_f32_e32 v124, 0, v129
	v_max_f32_e32 v125, 0, v125
	v_max_f32_e32 v126, 0, v126
	v_rsq_f32_e32 v164, v151
	v_mad_i64_i32 v[174:175], s[30:31], v150, s48, v[168:169]
	v_lshlrev_b64 v[150:151], 1, v[172:173]
	v_max_f32_e32 v128, 0, v128
	v_mul_f32_e32 v124, v124, v124
	v_mul_f32_e32 v129, v125, v125
	v_max_f32_e32 v125, 0, v130
	v_mul_f32_e32 v130, v126, v126
	v_max_f32_e32 v126, 0, v131
	v_max_f32_e32 v127, 0, v127
	v_pk_mul_f32 v[118:119], v[118:119], v[160:161] op_sel_hi:[1,0]
	v_pk_mul_f32 v[116:117], v[116:117], v[160:161] op_sel_hi:[1,0]
	v_lshl_add_u64 v[172:173], v[174:175], 0, v[150:151]
	v_mul_f32_e32 v128, v128, v128
	v_mul_f32_e32 v125, v125, v125
	v_mul_f32_e32 v126, v126, v126
	v_mul_f32_e32 v127, v127, v127
	v_cvt_pk_bf16_f32 v124, v128, v124
	v_pk_mul_f32 v[122:123], v[122:123], v[160:161] op_sel_hi:[1,0]
	v_pk_mul_f32 v[120:121], v[120:121], v[160:161] op_sel_hi:[1,0]
	v_max_f32_e32 v116, 0, v116
	v_max_f32_e32 v117, 0, v117
	v_max_f32_e32 v118, 0, v118
	v_cvt_pk_bf16_f32 v125, v125, v126
	v_cvt_pk_bf16_f32 v126, v153, v129
	v_cvt_pk_bf16_f32 v127, v130, v127
	global_store_dwordx4 v[172:173], v[124:127], off
	v_max_f32_e32 v120, 0, v120
	v_max_f32_e32 v119, 0, v119
	v_mul_f32_e32 v124, v116, v116
	v_max_f32_e32 v116, 0, v121
	v_mul_f32_e32 v121, v117, v117
	v_max_f32_e32 v117, 0, v122
	v_mul_f32_e32 v122, v118, v118
	v_max_f32_e32 v118, 0, v123
	v_mul_f32_e32 v116, v116, v116
	v_mul_f32_e32 v117, v117, v117
	v_mul_f32_e32 v118, v118, v118
	v_pk_mul_f32 v[108:109], v[108:109], v[158:159] op_sel_hi:[1,0]
	v_mul_f32_e32 v120, v120, v120
	v_mul_f32_e32 v119, v119, v119
	v_cvt_pk_bf16_f32 v116, v120, v116
	v_cvt_pk_bf16_f32 v117, v117, v118
	v_cvt_pk_bf16_f32 v118, v124, v121
	v_pk_mul_f32 v[112:113], v[112:113], v[158:159] op_sel_hi:[1,0]
	v_pk_mul_f32 v[110:111], v[110:111], v[158:159] op_sel_hi:[1,0]
	v_max_f32_e32 v108, 0, v108
	v_cvt_pk_bf16_f32 v119, v122, v119
	global_store_dwordx4 v[172:173], v[116:119], off offset:256
	v_pk_mul_f32 v[114:115], v[114:115], v[158:159] op_sel_hi:[1,0]
	v_max_f32_e32 v109, 0, v109
	v_mul_f32_e32 v118, v108, v108
	v_max_f32_e32 v108, 0, v113
	v_max_f32_e32 v110, 0, v110
	v_mad_i64_i32 v[116:117], s[30:31], v148, s48, v[168:169]
	v_max_f32_e32 v112, 0, v112
	v_mul_f32_e32 v108, v108, v108
	v_mul_f32_e32 v113, v109, v109
	v_max_f32_e32 v109, 0, v114
	v_mul_f32_e32 v114, v110, v110
	v_max_f32_e32 v110, 0, v115
	v_max_f32_e32 v111, 0, v111
	v_pk_mul_f32 v[102:103], v[102:103], v[158:159] op_sel_hi:[1,0]
	v_pk_mul_f32 v[100:101], v[100:101], v[158:159] op_sel_hi:[1,0]
	v_lshl_add_u64 v[116:117], v[116:117], 0, v[150:151]
	v_mul_f32_e32 v112, v112, v112
	v_mul_f32_e32 v109, v109, v109
	v_mul_f32_e32 v110, v110, v110
	v_mul_f32_e32 v111, v111, v111
	v_cvt_pk_bf16_f32 v108, v112, v108
	v_pk_mul_f32 v[106:107], v[106:107], v[158:159] op_sel_hi:[1,0]
	v_pk_mul_f32 v[104:105], v[104:105], v[158:159] op_sel_hi:[1,0]
	v_max_f32_e32 v100, 0, v100
	v_max_f32_e32 v101, 0, v101
	v_max_f32_e32 v102, 0, v102
	v_cvt_pk_bf16_f32 v109, v109, v110
	v_cvt_pk_bf16_f32 v110, v118, v113
	v_cvt_pk_bf16_f32 v111, v114, v111
	global_store_dwordx4 v[116:117], v[108:111], off
	v_max_f32_e32 v104, 0, v104
	v_max_f32_e32 v103, 0, v103
	v_mul_f32_e32 v108, v100, v100
	v_max_f32_e32 v100, 0, v105
	v_mul_f32_e32 v105, v101, v101
	v_max_f32_e32 v101, 0, v106
	v_mul_f32_e32 v106, v102, v102
	v_max_f32_e32 v102, 0, v107
	v_mul_f32_e32 v100, v100, v100
	v_mul_f32_e32 v101, v101, v101
	v_mul_f32_e32 v102, v102, v102
	v_pk_mul_f32 v[92:93], v[92:93], v[156:157] op_sel_hi:[1,0]
	v_mul_f32_e32 v104, v104, v104
	v_mul_f32_e32 v103, v103, v103
	v_cvt_pk_bf16_f32 v100, v104, v100
	v_cvt_pk_bf16_f32 v101, v101, v102
	v_cvt_pk_bf16_f32 v102, v108, v105
	v_pk_mul_f32 v[96:97], v[96:97], v[156:157] op_sel_hi:[1,0]
	v_pk_mul_f32 v[94:95], v[94:95], v[156:157] op_sel_hi:[1,0]
	v_max_f32_e32 v92, 0, v92
	v_cvt_pk_bf16_f32 v103, v106, v103
	global_store_dwordx4 v[116:117], v[100:103], off offset:256
	v_pk_mul_f32 v[98:99], v[98:99], v[156:157] op_sel_hi:[1,0]
	v_max_f32_e32 v93, 0, v93
	v_mul_f32_e32 v102, v92, v92
	v_max_f32_e32 v92, 0, v97
	v_max_f32_e32 v94, 0, v94
	v_mad_i64_i32 v[100:101], s[30:31], v146, s48, v[168:169]
	v_max_f32_e32 v96, 0, v96
	v_mul_f32_e32 v92, v92, v92
	v_mul_f32_e32 v97, v93, v93
	v_max_f32_e32 v93, 0, v98
	v_mul_f32_e32 v98, v94, v94
	v_max_f32_e32 v94, 0, v99
	v_max_f32_e32 v95, 0, v95
	v_pk_mul_f32 v[86:87], v[86:87], v[156:157] op_sel_hi:[1,0]
	v_pk_mul_f32 v[84:85], v[84:85], v[156:157] op_sel_hi:[1,0]
	v_lshl_add_u64 v[100:101], v[100:101], 0, v[150:151]
	v_mul_f32_e32 v96, v96, v96
	v_mul_f32_e32 v93, v93, v93
	v_mul_f32_e32 v94, v94, v94
	v_mul_f32_e32 v95, v95, v95
	v_cvt_pk_bf16_f32 v92, v96, v92
	v_pk_mul_f32 v[90:91], v[90:91], v[156:157] op_sel_hi:[1,0]
	v_pk_mul_f32 v[88:89], v[88:89], v[156:157] op_sel_hi:[1,0]
	v_max_f32_e32 v84, 0, v84
	v_max_f32_e32 v85, 0, v85
	v_max_f32_e32 v86, 0, v86
	v_cvt_pk_bf16_f32 v93, v93, v94
	v_cvt_pk_bf16_f32 v94, v102, v97
	v_cvt_pk_bf16_f32 v95, v98, v95
	global_store_dwordx4 v[100:101], v[92:95], off
	v_max_f32_e32 v88, 0, v88
	v_max_f32_e32 v87, 0, v87
	v_mul_f32_e32 v92, v84, v84
	v_max_f32_e32 v84, 0, v89
	v_mul_f32_e32 v89, v85, v85
	v_max_f32_e32 v85, 0, v90
	v_mul_f32_e32 v90, v86, v86
	v_max_f32_e32 v86, 0, v91
	v_mul_f32_e32 v84, v84, v84
	v_mul_f32_e32 v85, v85, v85
	v_mul_f32_e32 v86, v86, v86
	v_pk_mul_f32 v[76:77], v[76:77], v[154:155] op_sel_hi:[1,0]
	v_mul_f32_e32 v88, v88, v88
	v_mul_f32_e32 v87, v87, v87
	v_cvt_pk_bf16_f32 v84, v88, v84
	v_cvt_pk_bf16_f32 v85, v85, v86
	v_cvt_pk_bf16_f32 v86, v92, v89
	v_pk_mul_f32 v[80:81], v[80:81], v[154:155] op_sel_hi:[1,0]
	v_pk_mul_f32 v[78:79], v[78:79], v[154:155] op_sel_hi:[1,0]
	v_max_f32_e32 v76, 0, v76
	v_cvt_pk_bf16_f32 v87, v90, v87
	global_store_dwordx4 v[100:101], v[84:87], off offset:256
	v_pk_mul_f32 v[82:83], v[82:83], v[154:155] op_sel_hi:[1,0]
	v_max_f32_e32 v77, 0, v77
	v_mul_f32_e32 v86, v76, v76
	v_max_f32_e32 v76, 0, v81
	v_max_f32_e32 v78, 0, v78
	v_mad_i64_i32 v[84:85], s[30:31], v144, s48, v[168:169]
	v_max_f32_e32 v80, 0, v80
	v_mul_f32_e32 v76, v76, v76
	v_mul_f32_e32 v81, v77, v77
	v_max_f32_e32 v77, 0, v82
	v_mul_f32_e32 v82, v78, v78
	v_max_f32_e32 v78, 0, v83
	v_max_f32_e32 v79, 0, v79
	v_pk_mul_f32 v[70:71], v[70:71], v[154:155] op_sel_hi:[1,0]
	v_pk_mul_f32 v[68:69], v[68:69], v[154:155] op_sel_hi:[1,0]
	v_lshl_add_u64 v[84:85], v[84:85], 0, v[150:151]
	v_mul_f32_e32 v80, v80, v80
	v_mul_f32_e32 v77, v77, v77
	v_mul_f32_e32 v78, v78, v78
	v_mul_f32_e32 v79, v79, v79
	v_cvt_pk_bf16_f32 v76, v80, v76
	v_pk_mul_f32 v[74:75], v[74:75], v[154:155] op_sel_hi:[1,0]
	v_pk_mul_f32 v[72:73], v[72:73], v[154:155] op_sel_hi:[1,0]
	v_max_f32_e32 v68, 0, v68
	v_max_f32_e32 v69, 0, v69
	v_max_f32_e32 v70, 0, v70
	v_cvt_pk_bf16_f32 v77, v77, v78
	v_cvt_pk_bf16_f32 v78, v86, v81
	v_cvt_pk_bf16_f32 v79, v82, v79
	global_store_dwordx4 v[84:85], v[76:79], off
	v_max_f32_e32 v72, 0, v72
	v_max_f32_e32 v71, 0, v71
	v_mul_f32_e32 v76, v68, v68
	v_max_f32_e32 v68, 0, v73
	v_mul_f32_e32 v73, v69, v69
	v_max_f32_e32 v69, 0, v74
	v_mul_f32_e32 v74, v70, v70
	v_max_f32_e32 v70, 0, v75
	v_mul_f32_e32 v68, v68, v68
	v_mul_f32_e32 v69, v69, v69
	v_mul_f32_e32 v70, v70, v70
	v_pk_mul_f32 v[60:61], v[60:61], v[152:153] op_sel_hi:[1,0]
	v_mul_f32_e32 v72, v72, v72
	v_mul_f32_e32 v71, v71, v71
	v_cvt_pk_bf16_f32 v68, v72, v68
	v_cvt_pk_bf16_f32 v69, v69, v70
	v_cvt_pk_bf16_f32 v70, v76, v73
	v_pk_mul_f32 v[64:65], v[64:65], v[152:153] op_sel_hi:[1,0]
	v_pk_mul_f32 v[62:63], v[62:63], v[152:153] op_sel_hi:[1,0]
	v_max_f32_e32 v60, 0, v60
	v_cvt_pk_bf16_f32 v71, v74, v71
	global_store_dwordx4 v[84:85], v[68:71], off offset:256
	v_pk_mul_f32 v[66:67], v[66:67], v[152:153] op_sel_hi:[1,0]
	v_max_f32_e32 v61, 0, v61
	v_mul_f32_e32 v70, v60, v60
	v_max_f32_e32 v60, 0, v65
	v_max_f32_e32 v62, 0, v62
	v_mad_i64_i32 v[68:69], s[30:31], v170, s48, v[168:169]
	v_max_f32_e32 v64, 0, v64
	v_mul_f32_e32 v60, v60, v60
	v_mul_f32_e32 v65, v61, v61
	v_max_f32_e32 v61, 0, v66
	v_mul_f32_e32 v66, v62, v62
	v_max_f32_e32 v62, 0, v67
	v_max_f32_e32 v63, 0, v63
	v_pk_mul_f32 v[54:55], v[54:55], v[152:153] op_sel_hi:[1,0]
	v_pk_mul_f32 v[52:53], v[52:53], v[152:153] op_sel_hi:[1,0]
	v_lshl_add_u64 v[68:69], v[68:69], 0, v[150:151]
	v_mul_f32_e32 v64, v64, v64
	v_mul_f32_e32 v61, v61, v61
	v_mul_f32_e32 v62, v62, v62
	v_mul_f32_e32 v63, v63, v63
	v_cvt_pk_bf16_f32 v60, v64, v60
	v_pk_mul_f32 v[58:59], v[58:59], v[152:153] op_sel_hi:[1,0]
	v_pk_mul_f32 v[56:57], v[56:57], v[152:153] op_sel_hi:[1,0]
	v_max_f32_e32 v52, 0, v52
	v_max_f32_e32 v53, 0, v53
	v_max_f32_e32 v54, 0, v54
	v_cvt_pk_bf16_f32 v61, v61, v62
	v_cvt_pk_bf16_f32 v62, v70, v65
	v_cvt_pk_bf16_f32 v63, v66, v63
	global_store_dwordx4 v[68:69], v[60:63], off
	v_max_f32_e32 v56, 0, v56
	v_max_f32_e32 v55, 0, v55
	v_mul_f32_e32 v60, v52, v52
	v_max_f32_e32 v52, 0, v57
	v_mul_f32_e32 v57, v53, v53
	v_max_f32_e32 v53, 0, v58
	v_mul_f32_e32 v58, v54, v54
	v_max_f32_e32 v54, 0, v59
	v_mul_f32_e32 v52, v52, v52
	v_mul_f32_e32 v53, v53, v53
	v_mul_f32_e32 v54, v54, v54
	v_pk_mul_f32 v[44:45], v[44:45], v[162:163] op_sel_hi:[1,0]
	v_mul_f32_e32 v56, v56, v56
	v_mul_f32_e32 v55, v55, v55
	v_cvt_pk_bf16_f32 v52, v56, v52
	v_cvt_pk_bf16_f32 v53, v53, v54
	v_cvt_pk_bf16_f32 v54, v60, v57
	v_pk_mul_f32 v[48:49], v[48:49], v[162:163] op_sel_hi:[1,0]
	v_pk_mul_f32 v[46:47], v[46:47], v[162:163] op_sel_hi:[1,0]
	v_max_f32_e32 v44, 0, v44
	v_cvt_pk_bf16_f32 v55, v58, v55
	global_store_dwordx4 v[68:69], v[52:55], off offset:256
	v_pk_mul_f32 v[50:51], v[50:51], v[162:163] op_sel_hi:[1,0]
	v_max_f32_e32 v45, 0, v45
	v_mul_f32_e32 v54, v44, v44
	v_max_f32_e32 v44, 0, v49
	v_max_f32_e32 v46, 0, v46
	v_mad_i64_i32 v[52:53], s[30:31], v149, s48, v[168:169]
	v_max_f32_e32 v48, 0, v48
	v_mul_f32_e32 v44, v44, v44
	v_mul_f32_e32 v49, v45, v45
	v_max_f32_e32 v45, 0, v50
	v_mul_f32_e32 v50, v46, v46
	v_max_f32_e32 v46, 0, v51
	v_max_f32_e32 v47, 0, v47
	v_pk_mul_f32 v[38:39], v[38:39], v[162:163] op_sel_hi:[1,0]
	v_pk_mul_f32 v[36:37], v[36:37], v[162:163] op_sel_hi:[1,0]
	v_lshl_add_u64 v[52:53], v[52:53], 0, v[150:151]
	v_mul_f32_e32 v48, v48, v48
	v_mul_f32_e32 v45, v45, v45
	v_mul_f32_e32 v46, v46, v46
	v_mul_f32_e32 v47, v47, v47
	v_cvt_pk_bf16_f32 v44, v48, v44
	v_pk_mul_f32 v[42:43], v[42:43], v[162:163] op_sel_hi:[1,0]
	v_pk_mul_f32 v[40:41], v[40:41], v[162:163] op_sel_hi:[1,0]
	v_max_f32_e32 v36, 0, v36
	v_max_f32_e32 v37, 0, v37
	v_max_f32_e32 v38, 0, v38
	v_cvt_pk_bf16_f32 v45, v45, v46
	v_cvt_pk_bf16_f32 v46, v54, v49
	v_cvt_pk_bf16_f32 v47, v50, v47
	global_store_dwordx4 v[52:53], v[44:47], off
	v_max_f32_e32 v40, 0, v40
	v_max_f32_e32 v39, 0, v39
	v_mul_f32_e32 v44, v36, v36
	v_max_f32_e32 v36, 0, v41
	v_mul_f32_e32 v41, v37, v37
	v_max_f32_e32 v37, 0, v42
	v_mul_f32_e32 v42, v38, v38
	v_max_f32_e32 v38, 0, v43
	v_mul_f32_e32 v36, v36, v36
	v_mul_f32_e32 v37, v37, v37
	v_mul_f32_e32 v38, v38, v38
	v_pk_mul_f32 v[28:29], v[28:29], v[166:167] op_sel_hi:[1,0]
	v_mul_f32_e32 v40, v40, v40
	v_mul_f32_e32 v39, v39, v39
	v_cvt_pk_bf16_f32 v36, v40, v36
	v_cvt_pk_bf16_f32 v37, v37, v38
	v_cvt_pk_bf16_f32 v38, v44, v41
	v_pk_mul_f32 v[32:33], v[32:33], v[166:167] op_sel_hi:[1,0]
	v_pk_mul_f32 v[30:31], v[30:31], v[166:167] op_sel_hi:[1,0]
	v_max_f32_e32 v28, 0, v28
	v_cvt_pk_bf16_f32 v39, v42, v39
	global_store_dwordx4 v[52:53], v[36:39], off offset:256
	v_pk_mul_f32 v[34:35], v[34:35], v[166:167] op_sel_hi:[1,0]
	v_max_f32_e32 v29, 0, v29
	v_mul_f32_e32 v38, v28, v28
	v_max_f32_e32 v28, 0, v33
	v_max_f32_e32 v30, 0, v30
	v_mad_i64_i32 v[36:37], s[30:31], v147, s48, v[168:169]
	v_max_f32_e32 v32, 0, v32
	v_mul_f32_e32 v28, v28, v28
	v_mul_f32_e32 v33, v29, v29
	v_max_f32_e32 v29, 0, v34
	v_mul_f32_e32 v34, v30, v30
	v_max_f32_e32 v30, 0, v35
	v_max_f32_e32 v31, 0, v31
	v_pk_mul_f32 v[22:23], v[22:23], v[166:167] op_sel_hi:[1,0]
	v_pk_mul_f32 v[20:21], v[20:21], v[166:167] op_sel_hi:[1,0]
	v_lshl_add_u64 v[36:37], v[36:37], 0, v[150:151]
	v_mul_f32_e32 v32, v32, v32
	v_mul_f32_e32 v29, v29, v29
	v_mul_f32_e32 v30, v30, v30
	v_mul_f32_e32 v31, v31, v31
	v_cvt_pk_bf16_f32 v28, v32, v28
	v_pk_mul_f32 v[26:27], v[26:27], v[166:167] op_sel_hi:[1,0]
	v_pk_mul_f32 v[24:25], v[24:25], v[166:167] op_sel_hi:[1,0]
	v_max_f32_e32 v20, 0, v20
	v_max_f32_e32 v21, 0, v21
	v_max_f32_e32 v22, 0, v22
	v_cvt_pk_bf16_f32 v29, v29, v30
	v_cvt_pk_bf16_f32 v30, v38, v33
	v_cvt_pk_bf16_f32 v31, v34, v31
	global_store_dwordx4 v[36:37], v[28:31], off
	v_max_f32_e32 v24, 0, v24
	v_max_f32_e32 v23, 0, v23
	v_mul_f32_e32 v28, v20, v20
	v_max_f32_e32 v20, 0, v25
	v_mul_f32_e32 v25, v21, v21
	v_max_f32_e32 v21, 0, v26
	v_mul_f32_e32 v26, v22, v22
	v_max_f32_e32 v22, 0, v27
	v_mul_f32_e32 v20, v20, v20
	v_mul_f32_e32 v21, v21, v21
	v_mul_f32_e32 v22, v22, v22
	v_pk_mul_f32 v[12:13], v[12:13], v[164:165] op_sel_hi:[1,0]
	v_mul_f32_e32 v24, v24, v24
	v_mul_f32_e32 v23, v23, v23
	v_cvt_pk_bf16_f32 v20, v24, v20
	v_cvt_pk_bf16_f32 v21, v21, v22
	v_cvt_pk_bf16_f32 v22, v28, v25
	v_pk_mul_f32 v[16:17], v[16:17], v[164:165] op_sel_hi:[1,0]
	v_pk_mul_f32 v[14:15], v[14:15], v[164:165] op_sel_hi:[1,0]
	v_max_f32_e32 v12, 0, v12
	v_cvt_pk_bf16_f32 v23, v26, v23
	global_store_dwordx4 v[36:37], v[20:23], off offset:256
	v_pk_mul_f32 v[18:19], v[18:19], v[164:165] op_sel_hi:[1,0]
	v_max_f32_e32 v13, 0, v13
	v_mul_f32_e32 v22, v12, v12
	v_max_f32_e32 v12, 0, v17
	v_max_f32_e32 v14, 0, v14
	v_mad_i64_i32 v[20:21], s[30:31], v145, s48, v[168:169]
	v_max_f32_e32 v16, 0, v16
	v_mul_f32_e32 v12, v12, v12
	v_mul_f32_e32 v17, v13, v13
	v_max_f32_e32 v13, 0, v18
	v_mul_f32_e32 v18, v14, v14
	v_max_f32_e32 v14, 0, v19
	v_max_f32_e32 v15, 0, v15
	v_pk_mul_f32 v[6:7], v[6:7], v[164:165] op_sel_hi:[1,0]
	v_pk_mul_f32 v[4:5], v[4:5], v[164:165] op_sel_hi:[1,0]
	v_lshl_add_u64 v[20:21], v[20:21], 0, v[150:151]
	v_mul_f32_e32 v16, v16, v16
	v_mul_f32_e32 v13, v13, v13
	v_mul_f32_e32 v14, v14, v14
	v_mul_f32_e32 v15, v15, v15
	v_cvt_pk_bf16_f32 v12, v16, v12
	v_pk_mul_f32 v[10:11], v[10:11], v[164:165] op_sel_hi:[1,0]
	v_pk_mul_f32 v[8:9], v[8:9], v[164:165] op_sel_hi:[1,0]
	v_max_f32_e32 v4, 0, v4
	v_max_f32_e32 v5, 0, v5
	v_max_f32_e32 v6, 0, v6
	v_cvt_pk_bf16_f32 v13, v13, v14
	v_cvt_pk_bf16_f32 v14, v22, v17
	v_cvt_pk_bf16_f32 v15, v18, v15
	global_store_dwordx4 v[20:21], v[12:15], off
	v_max_f32_e32 v7, 0, v7
	v_max_f32_e32 v8, 0, v8
	v_mul_f32_e32 v12, v4, v4
	v_max_f32_e32 v4, 0, v9
	v_mul_f32_e32 v9, v5, v5
	v_max_f32_e32 v5, 0, v10
	v_mul_f32_e32 v10, v6, v6
	v_max_f32_e32 v6, 0, v11
	v_mul_f32_e32 v4, v4, v4
	v_mul_f32_e32 v5, v5, v5
	v_mul_f32_e32 v6, v6, v6
	v_mul_f32_e32 v7, v7, v7
	s_mov_b64 s[30:31], -1
	v_mul_f32_e32 v8, v8, v8
	v_cvt_pk_bf16_f32 v4, v8, v4
	v_cvt_pk_bf16_f32 v5, v5, v6
	v_cvt_pk_bf16_f32 v6, v12, v9
	v_cvt_pk_bf16_f32 v7, v10, v7
	global_store_dwordx4 v[20:21], v[4:7], off offset:256
	s_cbranch_vccnz .LBB0_1159
	s_setprio 2
	s_andn2_b64 vcc, exec, s[10:11]
	s_cbranch_vccnz .LBB0_1158
	s_setprio 0
	s_mov_b32 s100, 1
	s_branch .LBB0_1158

.LBB0_1189:
	v_lshl_add_u32 v140, s60, 8, v3
	v_ashrrev_i32_e32 v141, 31, v140
	v_lshl_or_b32 v152, s72, 8, v143
	v_or_b32_e32 v146, 16, v140
	v_or_b32_e32 v148, 32, v140
	v_or_b32_e32 v150, 48, v140
	v_ashrrev_i32_e32 v153, 31, v152
	v_lshlrev_b64 v[140:141], 12, v[140:141]
	v_lshl_add_u64 v[140:141], s[16:17], 0, v[140:141]
	v_lshlrev_b64 v[152:153], 1, v[152:153]
	v_ashrrev_i32_e32 v147, 31, v146
	v_lshl_add_u64 v[140:141], v[140:141], 0, v[152:153]
	v_cvt_pk_bf16_f32 v128, v128, v129
	v_cvt_pk_bf16_f32 v129, v130, v131
	v_cvt_pk_bf16_f32 v130, v124, v125
	v_cvt_pk_bf16_f32 v131, v126, v127
	global_store_dwordx4 v[140:141], v[128:131], off
	v_cvt_pk_bf16_f32 v116, v116, v117
	v_cvt_pk_bf16_f32 v117, v118, v119
	v_cvt_pk_bf16_f32 v118, v108, v109
	v_lshlrev_b64 v[108:109], 12, v[146:147]
	v_lshl_add_u64 v[108:109], s[16:17], 0, v[108:109]
	v_ashrrev_i32_e32 v149, 31, v148
	v_cvt_pk_bf16_f32 v119, v110, v111
	global_store_dwordx4 v[140:141], v[116:119], off offset:256
	v_ashrrev_i32_e32 v151, 31, v150
	s_mov_b32 s84, 0x80000
	v_lshl_add_u64 v[116:117], v[108:109], 0, v[152:153]
	v_cvt_pk_bf16_f32 v108, v120, v121
	v_cvt_pk_bf16_f32 v109, v122, v123
	v_cvt_pk_bf16_f32 v110, v112, v113
	v_cvt_pk_bf16_f32 v111, v114, v115
	global_store_dwordx4 v[116:117], v[108:111], off
	v_cvt_pk_bf16_f32 v100, v100, v101
	v_cvt_pk_bf16_f32 v101, v102, v103
	v_cvt_pk_bf16_f32 v102, v92, v93
	v_lshlrev_b64 v[92:93], 12, v[148:149]
	v_lshl_add_u64 v[92:93], s[16:17], 0, v[92:93]
	v_cvt_pk_bf16_f32 v103, v94, v95
	global_store_dwordx4 v[116:117], v[100:103], off offset:256
	s_mov_b64 s[30:31], 0x80000
	s_mov_b32 s85, 0x90000
	v_lshl_add_u64 v[100:101], v[92:93], 0, v[152:153]
	v_cvt_pk_bf16_f32 v92, v104, v105
	v_cvt_pk_bf16_f32 v93, v106, v107
	v_cvt_pk_bf16_f32 v94, v96, v97
	v_cvt_pk_bf16_f32 v95, v98, v99
	global_store_dwordx4 v[100:101], v[92:95], off
	v_cvt_pk_bf16_f32 v84, v84, v85
	v_cvt_pk_bf16_f32 v85, v86, v87
	v_cvt_pk_bf16_f32 v86, v76, v77
	v_lshlrev_b64 v[76:77], 12, v[150:151]
	v_lshl_add_u64 v[76:77], s[16:17], 0, v[76:77]
	v_cvt_pk_bf16_f32 v87, v78, v79
	global_store_dwordx4 v[100:101], v[84:87], off offset:256
	s_mov_b32 s0, 0xa0000
	s_nop 0
	v_lshl_add_u64 v[84:85], v[76:77], 0, v[152:153]
	v_cvt_pk_bf16_f32 v76, v88, v89
	v_cvt_pk_bf16_f32 v77, v90, v91
	v_cvt_pk_bf16_f32 v78, v80, v81
	v_cvt_pk_bf16_f32 v79, v82, v83
	global_store_dwordx4 v[84:85], v[76:79], off
	v_cvt_pk_bf16_f32 v72, v72, v73
	v_cvt_pk_bf16_f32 v73, v74, v75
	v_cvt_pk_bf16_f32 v74, v68, v69
	v_cvt_pk_bf16_f32 v75, v70, v71
	global_store_dwordx4 v[84:85], v[72:75], off offset:256
	v_cvt_pk_bf16_f32 v64, v64, v65
	v_cvt_pk_bf16_f32 v65, v66, v67
	v_cvt_pk_bf16_f32 v66, v60, v61
	v_add_co_u32_e32 v60, vcc, s84, v140
	v_lshl_add_u64 v[68:69], v[140:141], 0, s[30:31]
	s_nop 0
	v_addc_co_u32_e32 v61, vcc, 0, v141, vcc
	v_cvt_pk_bf16_f32 v67, v62, v63
	global_store_dwordx4 v[60:61], v[64:67], off
	v_cvt_pk_bf16_f32 v52, v52, v53
	v_cvt_pk_bf16_f32 v53, v54, v55
	v_cvt_pk_bf16_f32 v54, v44, v45
	v_cvt_pk_bf16_f32 v55, v46, v47
	global_store_dwordx4 v[68:69], v[52:55], off offset:256
	s_mov_b64 s[30:31], 0x90000
	v_cvt_pk_bf16_f32 v44, v56, v57
	v_cvt_pk_bf16_f32 v45, v58, v59
	v_cvt_pk_bf16_f32 v46, v48, v49
	v_add_co_u32_e32 v48, vcc, s85, v140
	v_lshl_add_u64 v[52:53], v[140:141], 0, s[30:31]
	s_nop 0
	v_addc_co_u32_e32 v49, vcc, 0, v141, vcc
	v_cvt_pk_bf16_f32 v47, v50, v51
	global_store_dwordx4 v[48:49], v[44:47], off
	v_cvt_pk_bf16_f32 v36, v36, v37
	v_cvt_pk_bf16_f32 v37, v38, v39
	v_cvt_pk_bf16_f32 v38, v28, v29
	v_cvt_pk_bf16_f32 v39, v30, v31
	global_store_dwordx4 v[52:53], v[36:39], off offset:256
	s_mov_b64 s[30:31], 0xa0000
	v_cvt_pk_bf16_f32 v28, v40, v41
	v_cvt_pk_bf16_f32 v29, v42, v43
	v_cvt_pk_bf16_f32 v30, v32, v33
	v_add_co_u32_e32 v32, vcc, s0, v140
	v_lshl_add_u64 v[36:37], v[140:141], 0, s[30:31]
	s_nop 0
	v_addc_co_u32_e32 v33, vcc, 0, v141, vcc
	s_mov_b32 s0, 0xb0000
	v_cvt_pk_bf16_f32 v31, v34, v35
	global_store_dwordx4 v[32:33], v[28:31], off
	v_cvt_pk_bf16_f32 v20, v20, v21
	v_cvt_pk_bf16_f32 v21, v22, v23
	v_cvt_pk_bf16_f32 v22, v12, v13
	v_cvt_pk_bf16_f32 v23, v14, v15
	global_store_dwordx4 v[36:37], v[20:23], off offset:256
	v_cvt_pk_bf16_f32 v12, v24, v25
	v_cvt_pk_bf16_f32 v13, v26, v27
	v_cvt_pk_bf16_f32 v14, v16, v17
	v_add_co_u32_e32 v16, vcc, s0, v140
	s_mov_b64 s[30:31], 0xb0000
	s_nop 0
	v_addc_co_u32_e32 v17, vcc, 0, v141, vcc
	v_lshl_add_u64 v[20:21], v[140:141], 0, s[30:31]
	s_andn2_b64 vcc, exec, s[10:11]
	s_mov_b64 s[10:11], -1
	v_cvt_pk_bf16_f32 v15, v18, v19
	global_store_dwordx4 v[16:17], v[12:15], off
	v_cvt_pk_bf16_f32 v8, v8, v9
	v_cvt_pk_bf16_f32 v9, v10, v11
	v_cvt_pk_bf16_f32 v10, v4, v5
	v_cvt_pk_bf16_f32 v11, v6, v7
	global_store_dwordx4 v[20:21], v[8:11], off offset:256
	s_cbranch_vccnz .LBB0_1182
	s_setprio 2
	s_andn2_b64 vcc, exec, s[14:15]
	s_cbranch_vccnz .LBB0_1181
	s_setprio 0
	s_mov_b32 s100, 1
	s_branch .LBB0_1181

.LBB0_1297:
	s_setprio 2
	s_andn2_b64 vcc, exec, s[16:17]
	s_cbranch_vccnz .LBB0_1257
	s_setprio 0
	s_mov_b32 s100, 1
	s_branch .LBB0_1257

.LBB0_1419:
	s_setprio 2
	s_andn2_b64 vcc, exec, s[74:75]
	s_cbranch_vccnz .LBB0_1386
	s_setprio 0
	s_mov_b32 s100, 1
	s_branch .LBB0_1386

	.amdhsa_kernel _Z7enc_fwd4Args
		.amdhsa_group_segment_fixed_size 0
		.amdhsa_private_segment_fixed_size 0
		.amdhsa_kernarg_size 512
		.amdhsa_user_sgpr_count 2
		.amdhsa_user_sgpr_dispatch_ptr 0
		.amdhsa_user_sgpr_queue_ptr 0
		.amdhsa_user_sgpr_kernarg_segment_ptr 1
		.amdhsa_user_sgpr_dispatch_id 0
		.amdhsa_user_sgpr_kernarg_preload_length 0
		.amdhsa_user_sgpr_kernarg_preload_offset 0
		.amdhsa_user_sgpr_private_segment_size 0
		.amdhsa_uses_dynamic_stack 0
		.amdhsa_enable_private_segment 0
		.amdhsa_system_sgpr_workgroup_id_x 1
		.amdhsa_system_sgpr_workgroup_id_y 0
		.amdhsa_system_sgpr_workgroup_id_z 0
		.amdhsa_system_sgpr_workgroup_info 0
		.amdhsa_system_vgpr_workitem_id 0
		.amdhsa_next_free_vgpr 256
		.amdhsa_next_free_sgpr 101
		.amdhsa_accum_offset 256
		.amdhsa_reserve_vcc 1
		.amdhsa_float_round_mode_32 0
		.amdhsa_float_round_mode_16_64 0
		.amdhsa_float_denorm_mode_32 3
		.amdhsa_float_denorm_mode_16_64 3
		.amdhsa_dx10_clamp 1
		.amdhsa_ieee_mode 1
		.amdhsa_fp16_overflow 0
		.amdhsa_tg_split 0
		.amdhsa_exception_fp_ieee_invalid_op 0
		.amdhsa_exception_fp_denorm_src 0
		.amdhsa_exception_fp_ieee_div_zero 0
		.amdhsa_exception_fp_ieee_overflow 0
		.amdhsa_exception_fp_ieee_underflow 0
		.amdhsa_exception_fp_ieee_inexact 0
		.amdhsa_exception_int_div_zero 0
	.end_amdhsa_kernel

amdhsa.kernels:
  - .agpr_count:     0
    .args:
      - .offset:         0
        .size:           256
        .value_kind:     by_value
      - .offset:         256
        .size:           4
        .value_kind:     hidden_block_count_x
      - .offset:         260
        .size:           4
        .value_kind:     hidden_block_count_y
      - .offset:         264
        .size:           4
        .value_kind:     hidden_block_count_z
      - .offset:         268
        .size:           2
        .value_kind:     hidden_group_size_x
      - .offset:         270
        .size:           2
        .value_kind:     hidden_group_size_y
      - .offset:         272
        .size:           2
        .value_kind:     hidden_group_size_z
      - .offset:         274
        .size:           2
        .value_kind:     hidden_remainder_x
      - .offset:         276
        .size:           2
        .value_kind:     hidden_remainder_y
      - .offset:         278
        .size:           2
        .value_kind:     hidden_remainder_z
      - .offset:         296
        .size:           8
        .value_kind:     hidden_global_offset_x
      - .offset:         304
        .size:           8
        .value_kind:     hidden_global_offset_y
      - .offset:         312
        .size:           8
        .value_kind:     hidden_global_offset_z
      - .offset:         320
        .size:           2
        .value_kind:     hidden_grid_dims
      - .offset:         376
        .size:           4
        .value_kind:     hidden_dynamic_lds_size
    .group_segment_fixed_size: 0
    .kernarg_segment_align: 8
    .kernarg_segment_size: 512
    .language:       OpenCL C
    .language_version:
      - 2
      - 0
    .max_flat_workgroup_size: 512
    .name:           _Z7enc_fwd4Args
    .private_segment_fixed_size: 0
    .sgpr_count:     107
    .sgpr_spill_count: 82
    .symbol:         _Z7enc_fwd4Args.kd
    .uniform_work_group_size: 1
    .uses_dynamic_stack: false
    .vgpr_count:     256
    .vgpr_spill_count: 0
    .wavefront_size: 64
